# diff attention fast path: exp/cvt interleaved with PV MFMAs (k2-outer), V fragments prefetched, scalar adds instead of pk_add
# speedup vs baseline: 1.0231x; 1.0231x over previous
; #define LAS __attribute__((address_space(3)))
; __device__ __forceinline__ float fexp2(float x) { return __builtin_amdgcn_exp2f(x); }
; template <int MODE, int DK, bool PASS2> ...
;     ...
;                 const LAS unsigned char* kb = lds + F_KB0 + buf * F_KBS + g * 16 + prow * KSTR;
;                 __builtin_amdgcn_s_setprio(1);
; #pragma unroll
;                 for (int kk = 0; kk < DK / 16; ++kk) {
;                     const bf16x8 a0 = *(const LAS bf16x8*)(kb + kk * 32);
;                     const bf16x8 a1 = *(const LAS bf16x8*)(kb + 32 * KSTR + kk * 32);
;                     s0 = mfma32(a0, qf[kk], s0); s1 = mfma32(a1, qf[kk], s1);
;                 }
;                 __builtin_amdgcn_s_setprio(0);
;                 const bool need_causal = pos_max > t_wmin;
;                 const bool need_bias = (MODE != M_FOX) && ((t_wmin - pos_max) < 128);
;                 const bool need_win = (MODE == M_WIN) && (t_wmax - pos_min >= 512);
;                 if (!PASS2 && !(need_causal || need_bias || need_win)) {
;                     float mx = fmaxf(s0[0], s1[0]);
; #pragma unroll
;                     for (int r = 1; r < 16; ++r) mx = fmax3(mx, s0[r], s1[r]);
;                     if (MODE == M_SLC) mx = selbit ? mx : NEG;
;                     mx = xhalf_max(mx);
;                     const float mxs = mx * sl2;
;                     const float mn = (mxs > m_run + 8.0f) ? mxs : m_run;
;                     const float alpha = fexp2(m_run - mn);
;                     m_run = mn;
;                     float nm = -mn;
;                     if (MODE == M_SLC) nm = selbit ? nm : -__builtin_inff();
;                     float ps0 = 0.f, ps1 = 0.f;
; #pragma unroll
;                     for (int r = 0; r < 16; ++r) {
;                         s0[r] = fexp2(__builtin_fmaf(s0[r], sl2, nm)); s1[r] = fexp2(__builtin_fmaf(s1[r], sl2, nm));
;                         ps0 += s0[r]; ps1 += s1[r];
;                     }
;                     l_run = l_run * alpha + (ps0 + ps1);
;                     if (__builtin_amdgcn_ballot_w64(alpha != 1.0f) != 0ull) {
; #pragma unroll
;                         for (int db = 0; db < 4; ++db)
; #pragma unroll
;                             for (int r = 0; r < 16; ++r) O[db][r] *= alpha;
;                     }
.LBB0_2131:
	s_mul_i32 s4, s58, 0x4400
	v_add_u32_e32 v16, s4, v202
	s_setprio 1
	ds_read_b128 v[4:7], v16
	ds_read_b128 v[8:11], v16 offset:32
	s_waitcnt lgkmcnt(1)
	v_mfma_f32_32x32x16_bf16 v[82:97], v[4:7], v[114:117], 0
	ds_read_b128 v[4:7], v16 offset:4608
	ds_read_b128 v[12:15], v16 offset:4640
	s_waitcnt lgkmcnt(1)
	v_mfma_f32_32x32x16_bf16 v[98:113], v[4:7], v[114:117], 0
	v_mfma_f32_32x32x16_bf16 v[82:97], v[8:11], v[118:121], v[82:97]
	ds_read_b128 v[4:7], v16 offset:64
	ds_read_b128 v[8:11], v16 offset:96
	s_waitcnt lgkmcnt(2)
	v_mfma_f32_32x32x16_bf16 v[98:113], v[12:15], v[118:121], v[98:113]
	s_waitcnt lgkmcnt(1)
	v_mfma_f32_32x32x16_bf16 v[82:97], v[4:7], v[122:125], v[82:97]
	ds_read_b128 v[4:7], v16 offset:4672
	ds_read_b128 v[12:15], v16 offset:4704
	s_waitcnt lgkmcnt(1)
	v_mfma_f32_32x32x16_bf16 v[98:113], v[4:7], v[122:125], v[98:113]
	v_mfma_f32_32x32x16_bf16 v[82:97], v[8:11], v[126:129], v[82:97]
	s_waitcnt lgkmcnt(0)
	v_mfma_f32_32x32x16_bf16 v[98:113], v[12:15], v[126:129], v[98:113]
	s_setprio 0
	v_add_u32_e32 v4, s8, v196
	v_cmp_le_i32_e32 vcc, s57, v193
	v_cmp_lt_i32_e64 s[6:7], s52, v4
	v_cmp_gt_i32_e64 s[4:5], s51, v4
	s_and_b64 s[6:7], vcc, s[6:7]
	v_add_f32_e32 v208, 0x41000000, v178
	s_and_saveexec_b64 s[28:29], s[6:7]
	s_xor_b64 s[6:7], exec, s[28:29]
	s_cbranch_execz .LBB0_2135
	s_cmp_eq_u64 s[6:7], 0
	s_cbranch_scc1 .Lfast_diff
	s_nop 1
	v_max_f32_e32 v4, v98, v98
	v_max_f32_e32 v5, v82, v82
	v_max_f32_e32 v4, v5, v4
	v_max3_f32 v4, v4, v83, v99
	s_nop 0
	v_max3_f32 v4, v4, v84, v100
	s_nop 0
	v_max3_f32 v4, v4, v85, v101
	s_nop 0
	v_max3_f32 v4, v4, v86, v102
	s_nop 0
	v_max3_f32 v4, v4, v87, v103
	s_nop 0
	v_max3_f32 v4, v4, v88, v104
	s_nop 0
	v_max3_f32 v4, v4, v89, v105
	s_nop 0
	v_max3_f32 v4, v4, v90, v106
	s_nop 0
	v_max3_f32 v4, v4, v91, v107
	s_nop 0
	v_max3_f32 v4, v4, v92, v108
	s_nop 0
	v_max3_f32 v4, v4, v93, v109
	s_nop 0
	v_max3_f32 v4, v4, v94, v110
	s_nop 0
	v_max3_f32 v4, v4, v95, v111
	s_nop 0
	v_max3_f32 v4, v4, v96, v112
	s_nop 0
	v_max3_f32 v4, v4, v97, v113
	s_nop 0
	v_mov_b32_e32 v5, v4
	s_nop 1
	v_permlane32_swap_b32_e32 v4, v5
	v_max_f32_e32 v5, v5, v5
	v_max_f32_e32 v4, v4, v4
	v_max_f32_e32 v4, v4, v5
	v_mul_f32_e32 v4, 0x3e38aa3b, v4
	v_cmp_gt_f32_e32 vcc, v4, v208
	s_nop 1
	v_cndmask_b32_e32 v207, v178, v4, vcc
	v_sub_f32_e32 v4, v178, v207
	v_exp_f32_e32 v178, v4
	s_nop 0
	v_cmp_neq_f32_e32 vcc, 1.0, v178
	s_cbranch_vccz .LBB0_2134
	v_pk_mul_f32 v[80:81], v[80:81], v[178:179] op_sel_hi:[1,0]
	v_pk_mul_f32 v[78:79], v[78:79], v[178:179] op_sel_hi:[1,0]
	v_pk_mul_f32 v[76:77], v[76:77], v[178:179] op_sel_hi:[1,0]
	v_pk_mul_f32 v[74:75], v[74:75], v[178:179] op_sel_hi:[1,0]
	v_pk_mul_f32 v[72:73], v[72:73], v[178:179] op_sel_hi:[1,0]
	v_pk_mul_f32 v[70:71], v[70:71], v[178:179] op_sel_hi:[1,0]
	v_pk_mul_f32 v[68:69], v[68:69], v[178:179] op_sel_hi:[1,0]
	v_pk_mul_f32 v[66:67], v[66:67], v[178:179] op_sel_hi:[1,0]
	v_pk_mul_f32 v[64:65], v[64:65], v[178:179] op_sel_hi:[1,0]
	v_pk_mul_f32 v[62:63], v[62:63], v[178:179] op_sel_hi:[1,0]
	v_pk_mul_f32 v[60:61], v[60:61], v[178:179] op_sel_hi:[1,0]
	v_pk_mul_f32 v[58:59], v[58:59], v[178:179] op_sel_hi:[1,0]
	v_pk_mul_f32 v[56:57], v[56:57], v[178:179] op_sel_hi:[1,0]
	v_pk_mul_f32 v[54:55], v[54:55], v[178:179] op_sel_hi:[1,0]
	v_pk_mul_f32 v[52:53], v[52:53], v[178:179] op_sel_hi:[1,0]
	v_pk_mul_f32 v[50:51], v[50:51], v[178:179] op_sel_hi:[1,0]
	v_pk_mul_f32 v[48:49], v[48:49], v[178:179] op_sel_hi:[1,0]
	v_pk_mul_f32 v[46:47], v[46:47], v[178:179] op_sel_hi:[1,0]
	v_pk_mul_f32 v[44:45], v[44:45], v[178:179] op_sel_hi:[1,0]
	v_pk_mul_f32 v[42:43], v[42:43], v[178:179] op_sel_hi:[1,0]
	v_pk_mul_f32 v[40:41], v[40:41], v[178:179] op_sel_hi:[1,0]
	v_pk_mul_f32 v[38:39], v[38:39], v[178:179] op_sel_hi:[1,0]
	v_pk_mul_f32 v[36:37], v[36:37], v[178:179] op_sel_hi:[1,0]
	v_pk_mul_f32 v[34:35], v[34:35], v[178:179] op_sel_hi:[1,0]
	v_pk_mul_f32 v[32:33], v[32:33], v[178:179] op_sel_hi:[1,0]
	v_pk_mul_f32 v[30:31], v[30:31], v[178:179] op_sel_hi:[1,0]
	v_pk_mul_f32 v[28:29], v[28:29], v[178:179] op_sel_hi:[1,0]
	v_pk_mul_f32 v[26:27], v[26:27], v[178:179] op_sel_hi:[1,0]
	v_pk_mul_f32 v[24:25], v[24:25], v[178:179] op_sel_hi:[1,0]
	v_pk_mul_f32 v[22:23], v[22:23], v[178:179] op_sel_hi:[1,0]
	v_pk_mul_f32 v[20:21], v[20:21], v[178:179] op_sel_hi:[1,0]
	v_pk_mul_f32 v[18:19], v[18:19], v[178:179] op_sel_hi:[1,0]

; template <int MODE, int DK, bool PASS2> ...
;     ...
;         if (has) write_tile(buf ^ 1);
;         if (MODE == M_FOX) { if (__syncthreads_and(dead ? 1 : 0)) break; }
;         else __syncthreads();
;         if (!has) break;
;         j = jn; buf ^= 1;
.Lpostpv_diff:
	v_mov_b32_e32 v206, v209
	v_mov_b32_e32 v178, v207
	s_or_b64 exec, exec, s[26:27]
	s_andn2_b64 vcc, exec, s[24:25]
	s_xor_b32 s58, s58, 1
	s_cbranch_vccnz .LBB0_2126

; #define LAS __attribute__((address_space(3)))
; __device__ __forceinline__ float fexp2(float x) { return __builtin_amdgcn_exp2f(x); }
; __device__ __forceinline__ float fmax3(float a, float b, float c) { float d; asm("v_max3_f32 %0, %1, %2, %3" : "=v"(d) : "v"(a), "v"(b), "v"(c)); return d; }
; template <int MODE, int DK, bool PASS2> ...
;     ...
;                     float mx = fmaxf(s0[0], s1[0]);
; #pragma unroll
;                     for (int r = 1; r < 16; ++r) mx = fmax3(mx, s0[r], s1[r]);
;                     if (MODE == M_SLC) mx = selbit ? mx : NEG;
;                     mx = xhalf_max(mx);
;                     const float mxs = mx * sl2;
;                     const float mn = (mxs > m_run + 8.0f) ? mxs : m_run;
;                     const float alpha = fexp2(m_run - mn);
;                     m_run = mn;
;                     float nm = -mn;
;                     if (MODE == M_SLC) nm = selbit ? nm : -__builtin_inff();
;                     float ps0 = 0.f, ps1 = 0.f;
; #pragma unroll
;                     for (int r = 0; r < 16; ++r) {
;                         s0[r] = fexp2(__builtin_fmaf(s0[r], sl2, nm)); s1[r] = fexp2(__builtin_fmaf(s1[r], sl2, nm));
;                         ps0 += s0[r]; ps1 += s1[r];
;                     }
;                     l_run = l_run * alpha + (ps0 + ps1);
;                     if (__builtin_amdgcn_ballot_w64(alpha != 1.0f) != 0ull) {
; #pragma unroll
;                         for (int db = 0; db < 4; ++db)
; #pragma unroll
;                             for (int r = 0; r < 16; ++r) O[db][r] *= alpha;
;                     }
;     ...
;                     const LAS unsigned char* vb = lds + F_VB0 + buf * F_VBS + ql * 144 + g * 16;
;                     __builtin_amdgcn_s_setprio(1);
; #pragma unroll
;                     for (int db = 0; db < 4; ++db)
; #pragma unroll
;                         for (int k2 = 0; k2 < 4; ++k2) {
;                             const bf16x8 vf = *(const LAS bf16x8*)(vb + db * 32 * 144 + k2 * 32);
.Lfast_diff:
	s_mul_i32 s4, s58, 0x4800
	v_add_u32_e32 v210, s4, v201
	ds_read_b128 v[212:215], v210 offset:34816
	ds_read_b128 v[216:219], v210 offset:39424
	ds_read_b128 v[220:223], v210 offset:44032
	ds_read_b128 v[224:227], v210 offset:48640
	ds_read_b128 v[228:231], v210 offset:34848
	ds_read_b128 v[232:235], v210 offset:39456
	v_max_f32_e32 v160, v82, v98
	v_max_f32_e32 v161, v90, v106
	v_max3_f32 v160, v160, v83, v99
	v_max3_f32 v161, v161, v91, v107
	v_max3_f32 v160, v160, v84, v100
	v_max3_f32 v161, v161, v92, v108
	v_max3_f32 v160, v160, v85, v101
	v_max3_f32 v161, v161, v93, v109
	v_max3_f32 v160, v160, v86, v102
	v_max3_f32 v161, v161, v94, v110
	v_max3_f32 v160, v160, v87, v103
	v_max3_f32 v161, v161, v95, v111
	v_max3_f32 v160, v160, v88, v104
	v_max3_f32 v161, v161, v96, v112
	v_max3_f32 v160, v160, v89, v105
	v_max3_f32 v161, v161, v97, v113
	v_max_f32_e32 v160, v160, v161
	v_mov_b32_e32 v161, v160
	s_nop 1
	v_permlane32_swap_b32_e32 v160, v161
	v_max_f32_e32 v160, v160, v161
	v_mul_f32_e32 v160, 0x3e38aa3b, v160
	v_cmp_gt_f32_e32 vcc, v160, v208
	s_nop 1
	v_cndmask_b32_e32 v207, v178, v160, vcc
	v_sub_f32_e32 v161, v178, v207
	v_exp_f32_e32 v178, v161
	s_nop 0
	v_cmp_neq_f32_e32 vcc, 1.0, v178
	s_cbranch_vccz .Lfast_diff_norescale
	v_pk_mul_f32 v[66:67], v[66:67], v[178:179] op_sel_hi:[1,0]
	v_pk_mul_f32 v[68:69], v[68:69], v[178:179] op_sel_hi:[1,0]
	v_pk_mul_f32 v[70:71], v[70:71], v[178:179] op_sel_hi:[1,0]
	v_pk_mul_f32 v[72:73], v[72:73], v[178:179] op_sel_hi:[1,0]
	v_pk_mul_f32 v[74:75], v[74:75], v[178:179] op_sel_hi:[1,0]
	v_pk_mul_f32 v[76:77], v[76:77], v[178:179] op_sel_hi:[1,0]
	v_pk_mul_f32 v[78:79], v[78:79], v[178:179] op_sel_hi:[1,0]
	v_pk_mul_f32 v[80:81], v[80:81], v[178:179] op_sel_hi:[1,0]
	v_pk_mul_f32 v[50:51], v[50:51], v[178:179] op_sel_hi:[1,0]
	v_pk_mul_f32 v[52:53], v[52:53], v[178:179] op_sel_hi:[1,0]
	v_pk_mul_f32 v[54:55], v[54:55], v[178:179] op_sel_hi:[1,0]
	v_pk_mul_f32 v[56:57], v[56:57], v[178:179] op_sel_hi:[1,0]
	v_pk_mul_f32 v[58:59], v[58:59], v[178:179] op_sel_hi:[1,0]
	v_pk_mul_f32 v[60:61], v[60:61], v[178:179] op_sel_hi:[1,0]
	v_pk_mul_f32 v[62:63], v[62:63], v[178:179] op_sel_hi:[1,0]
	v_pk_mul_f32 v[64:65], v[64:65], v[178:179] op_sel_hi:[1,0]
	v_pk_mul_f32 v[34:35], v[34:35], v[178:179] op_sel_hi:[1,0]
	v_pk_mul_f32 v[36:37], v[36:37], v[178:179] op_sel_hi:[1,0]
	v_pk_mul_f32 v[38:39], v[38:39], v[178:179] op_sel_hi:[1,0]
	v_pk_mul_f32 v[40:41], v[40:41], v[178:179] op_sel_hi:[1,0]
	v_pk_mul_f32 v[42:43], v[42:43], v[178:179] op_sel_hi:[1,0]
	v_pk_mul_f32 v[44:45], v[44:45], v[178:179] op_sel_hi:[1,0]
	v_pk_mul_f32 v[46:47], v[46:47], v[178:179] op_sel_hi:[1,0]
	v_pk_mul_f32 v[48:49], v[48:49], v[178:179] op_sel_hi:[1,0]
	v_pk_mul_f32 v[18:19], v[18:19], v[178:179] op_sel_hi:[1,0]
	v_pk_mul_f32 v[20:21], v[20:21], v[178:179] op_sel_hi:[1,0]
	v_pk_mul_f32 v[22:23], v[22:23], v[178:179] op_sel_hi:[1,0]
	v_pk_mul_f32 v[24:25], v[24:25], v[178:179] op_sel_hi:[1,0]
	v_pk_mul_f32 v[26:27], v[26:27], v[178:179] op_sel_hi:[1,0]
	v_pk_mul_f32 v[28:29], v[28:29], v[178:179] op_sel_hi:[1,0]
	v_pk_mul_f32 v[30:31], v[30:31], v[178:179] op_sel_hi:[1,0]
	v_pk_mul_f32 v[32:33], v[32:33], v[178:179] op_sel_hi:[1,0]
; #define LAS __attribute__((address_space(3)))
; __device__ __forceinline__ unsigned pack2(float lo, float hi) { unsigned r; asm volatile("v_cvt_pk_bf16_f32 %0, %1, %2" : "=v"(r) : "v"(lo), "v"(hi)); return r; }
; __device__ __forceinline__ float fexp2(float x) { return __builtin_amdgcn_exp2f(x); }
; __device__ __forceinline__ f32x16 mfma32(bf16x8 a, bf16x8 b, f32x16 c) { return __builtin_amdgcn_mfma_f32_32x32x16_bf16(a, b, c, 0, 0, 0); }
; template <int MODE, int DK, bool PASS2> ...
;     ...
;                     float ps0 = 0.f, ps1 = 0.f;
; #pragma unroll
;                     for (int r = 0; r < 16; ++r) {
;                         s0[r] = fexp2(__builtin_fmaf(s0[r], sl2, nm)); s1[r] = fexp2(__builtin_fmaf(s1[r], sl2, nm));
;                         ps0 += s0[r]; ps1 += s1[r];
;                     }
;                     l_run = l_run * alpha + (ps0 + ps1);
;     ...
;                 if (!PASS2) {
;                     bf16x8 pf[4];
; #pragma unroll
;                     for (int k2 = 0; k2 < 4; ++k2) {
;                         u32x4 pk;
; #pragma unroll
;                         for (int e = 0; e < 4; ++e) pk[e] = (k2 < 2) ? pack2(s0[(k2 & 1) * 8 + 2 * e], s0[(k2 & 1) * 8 + 2 * e + 1]) : pack2(s1[(k2 & 1) * 8 + 2 * e], s1[(k2 & 1) * 8 + 2 * e + 1]);
;                         pf[k2] = __builtin_bit_cast(bf16x8, pk);
;                     }
;                     const LAS unsigned char* vb = lds + F_VB0 + buf * F_VBS + ql * 144 + g * 16;
;                     __builtin_amdgcn_s_setprio(1);
; #pragma unroll
;                     for (int db = 0; db < 4; ++db)
; #pragma unroll
;                         for (int k2 = 0; k2 < 4; ++k2) {
;                             const bf16x8 vf = *(const LAS bf16x8*)(vb + db * 32 * 144 + k2 * 32);
;                             O[db] = mfma32(vf, pf[k2], O[db]);
;                             if (k2 == 3 && (db & 1)) __builtin_amdgcn_sched_barrier(0);
;                         }
;                     __builtin_amdgcn_s_setprio(0);
.Lfast_diff_norescale:
	v_fma_f32 v12, v82, s12, -v207
	v_fma_f32 v13, v83, s12, -v207
	v_exp_f32_e32 v4, v12
	v_exp_f32_e32 v5, v13
	v_fma_f32 v14, v84, s12, -v207
	v_fma_f32 v15, v85, s12, -v207
	v_exp_f32_e32 v6, v14
	v_exp_f32_e32 v7, v15
	v_add_f32_e32 v16, v4, v5
	v_fma_f32 v12, v86, s12, -v207
	v_fma_f32 v13, v87, s12, -v207
	v_exp_f32_e32 v8, v12
	v_exp_f32_e32 v9, v13
	v_cvt_pk_bf16_f32 v236, v4, v5
	v_add_f32_e32 v16, v16, v6
	v_fma_f32 v14, v88, s12, -v207
	v_add_f32_e32 v16, v16, v7
	v_fma_f32 v15, v89, s12, -v207
	v_exp_f32_e32 v10, v14
	v_exp_f32_e32 v11, v15
	v_cvt_pk_bf16_f32 v237, v6, v7
	v_add_f32_e32 v16, v16, v8
	v_add_f32_e32 v16, v16, v9
	v_cvt_pk_bf16_f32 v238, v8, v9
	v_add_f32_e32 v16, v16, v10
	v_add_f32_e32 v16, v16, v11
	v_cvt_pk_bf16_f32 v239, v10, v11
	s_setprio 1
	v_fma_f32 v12, v90, s12, -v207
	v_fma_f32 v13, v91, s12, -v207
	s_waitcnt lgkmcnt(5)
	v_mfma_f32_32x32x16_bf16 v[66:81], v[212:215], v[236:239], v[66:81]
	v_exp_f32_e32 v4, v12
	v_exp_f32_e32 v5, v13
	v_fma_f32 v14, v92, s12, -v207
	v_fma_f32 v15, v93, s12, -v207
	v_exp_f32_e32 v6, v14
	v_exp_f32_e32 v7, v15
	v_add_f32_e32 v16, v16, v4
	s_waitcnt lgkmcnt(4)
	v_mfma_f32_32x32x16_bf16 v[50:65], v[216:219], v[236:239], v[50:65]
	ds_read_b128 v[212:215], v210 offset:44064
	v_fma_f32 v12, v94, s12, -v207
	v_add_f32_e32 v16, v16, v5
	v_fma_f32 v13, v95, s12, -v207
	v_exp_f32_e32 v8, v12
	v_exp_f32_e32 v9, v13
	v_cvt_pk_bf16_f32 v240, v4, v5
	v_add_f32_e32 v16, v16, v6
	s_waitcnt lgkmcnt(4)
	v_mfma_f32_32x32x16_bf16 v[34:49], v[220:223], v[236:239], v[34:49]
	ds_read_b128 v[216:219], v210 offset:48672
	v_fma_f32 v14, v96, s12, -v207
	v_add_f32_e32 v16, v16, v7
	v_fma_f32 v15, v97, s12, -v207
	v_exp_f32_e32 v10, v14
	v_exp_f32_e32 v11, v15
	v_cvt_pk_bf16_f32 v241, v6, v7
	v_add_f32_e32 v16, v16, v8
	s_waitcnt lgkmcnt(4)
	v_mfma_f32_32x32x16_bf16 v[18:33], v[224:227], v[236:239], v[18:33]
	ds_read_b128 v[220:223], v210 offset:34880
	v_add_f32_e32 v16, v16, v9
	v_cvt_pk_bf16_f32 v242, v8, v9
	v_add_f32_e32 v16, v16, v10
	v_add_f32_e32 v16, v16, v11
	v_cvt_pk_bf16_f32 v243, v10, v11
	v_fma_f32 v12, v98, s12, -v207
	v_fma_f32 v13, v99, s12, -v207
	s_waitcnt lgkmcnt(4)
	v_mfma_f32_32x32x16_bf16 v[66:81], v[228:231], v[240:243], v[66:81]
	ds_read_b128 v[224:227], v210 offset:39488
	v_exp_f32_e32 v4, v12
	v_exp_f32_e32 v5, v13
	v_fma_f32 v14, v100, s12, -v207
	v_fma_f32 v15, v101, s12, -v207
	v_exp_f32_e32 v6, v14
	v_exp_f32_e32 v7, v15
	v_add_f32_e32 v17, v4, v5
	s_waitcnt lgkmcnt(4)
	v_mfma_f32_32x32x16_bf16 v[50:65], v[232:235], v[240:243], v[50:65]
	ds_read_b128 v[228:231], v210 offset:44096
	v_fma_f32 v12, v102, s12, -v207
	v_fma_f32 v13, v103, s12, -v207
	v_exp_f32_e32 v8, v12
	v_exp_f32_e32 v9, v13
	v_cvt_pk_bf16_f32 v244, v4, v5
	v_add_f32_e32 v17, v17, v6
	v_fma_f32 v14, v104, s12, -v207
	s_waitcnt lgkmcnt(4)
	v_mfma_f32_32x32x16_bf16 v[34:49], v[212:215], v[240:243], v[34:49]
	ds_read_b128 v[232:235], v210 offset:48704
	v_add_f32_e32 v17, v17, v7
	v_fma_f32 v15, v105, s12, -v207
	v_exp_f32_e32 v10, v14
	v_exp_f32_e32 v11, v15
	v_cvt_pk_bf16_f32 v245, v6, v7
	v_add_f32_e32 v17, v17, v8
	v_add_f32_e32 v17, v17, v9
	s_waitcnt lgkmcnt(4)
	v_mfma_f32_32x32x16_bf16 v[18:33], v[216:219], v[240:243], v[18:33]
	ds_read_b128 v[212:215], v210 offset:34912
	v_cvt_pk_bf16_f32 v246, v8, v9
	v_add_f32_e32 v17, v17, v10
	v_add_f32_e32 v17, v17, v11
	v_cvt_pk_bf16_f32 v247, v10, v11
	v_fma_f32 v12, v106, s12, -v207
	v_fma_f32 v13, v107, s12, -v207
	s_waitcnt lgkmcnt(4)
	v_mfma_f32_32x32x16_bf16 v[66:81], v[220:223], v[244:247], v[66:81]
	ds_read_b128 v[216:219], v210 offset:39520
	v_exp_f32_e32 v4, v12
	v_exp_f32_e32 v5, v13
	v_fma_f32 v14, v108, s12, -v207
	v_fma_f32 v15, v109, s12, -v207
	v_exp_f32_e32 v6, v14
	v_exp_f32_e32 v7, v15
	v_add_f32_e32 v17, v17, v4
	s_waitcnt lgkmcnt(4)
	v_mfma_f32_32x32x16_bf16 v[50:65], v[224:227], v[244:247], v[50:65]
	ds_read_b128 v[220:223], v210 offset:44128
	v_fma_f32 v12, v110, s12, -v207
	v_add_f32_e32 v17, v17, v5
	v_fma_f32 v13, v111, s12, -v207
	v_exp_f32_e32 v8, v12
	v_exp_f32_e32 v9, v13
	v_cvt_pk_bf16_f32 v248, v4, v5
	v_add_f32_e32 v17, v17, v6
	s_waitcnt lgkmcnt(4)
	v_mfma_f32_32x32x16_bf16 v[34:49], v[228:231], v[244:247], v[34:49]
	ds_read_b128 v[224:227], v210 offset:48736
	v_fma_f32 v14, v112, s12, -v207
	v_add_f32_e32 v17, v17, v7
	v_fma_f32 v15, v113, s12, -v207
	v_exp_f32_e32 v10, v14
	v_exp_f32_e32 v11, v15
	v_cvt_pk_bf16_f32 v249, v6, v7
	v_add_f32_e32 v17, v17, v8
	s_waitcnt lgkmcnt(4)
	v_mfma_f32_32x32x16_bf16 v[18:33], v[232:235], v[244:247], v[18:33]
	v_add_f32_e32 v17, v17, v9
	v_cvt_pk_bf16_f32 v250, v8, v9
	v_add_f32_e32 v17, v17, v10
	v_add_f32_e32 v17, v17, v11
	v_cvt_pk_bf16_f32 v251, v10, v11
	v_add_f32_e32 v209, v16, v17
	s_waitcnt lgkmcnt(3)
	v_mfma_f32_32x32x16_bf16 v[66:81], v[212:215], v[248:251], v[66:81]
	v_fmac_f32_e32 v209, v206, v178
	s_waitcnt lgkmcnt(2)
	v_mfma_f32_32x32x16_bf16 v[50:65], v[216:219], v[248:251], v[50:65]
	s_waitcnt lgkmcnt(1)
	v_mfma_f32_32x32x16_bf16 v[34:49], v[220:223], v[248:251], v[34:49]
	s_waitcnt lgkmcnt(0)
	v_mfma_f32_32x32x16_bf16 v[18:33], v[224:227], v[248:251], v[18:33]
	s_setprio 0
	s_branch .Lpostpv_diff
